# v22 + nt hint on recur1 (hgrn_pass1/ssd_pass1) dwordx4 PROJ tile loads
# speedup vs baseline: 1.0066x; 1.0009x over previous
; #define LAS __attribute__((address_space(3)))
; #define LAUNDER_PTR(p) do {} while (0)
; #define LAUNDER_PTR(p) asm volatile("" : "+v"(p))
; __device__ __forceinline__ void ssd_pass1(const RecurBufs& rb, const float* conv_w, const float* conv_b, const float* dt_bias, const float* a_log, float* conv_out_l, int u, int tid, LAS unsigned char* lds) {
;     ...
;     const int ch16 = tid & 63, rr = tid >> 6;
;     const int gcol = ssd_gcol(grp, ch16);
;     LAS unsigned char* XO = lds + SD_XO;
;     v4u raw[8];
;     {   const bf16* gp = rb.proj + (rowS + rr) * LDP + PC_XBC + gcol;
; #pragma unroll
;         for (int i = 0; i < 8; ++i) { LAUNDER_PTR(gp); raw[i] = *(const v4u*)gp; gp += 8 * (size_t)LDP; } }
;     bf16 dtn = 0;
;     if (w < 4) dtn = rb.proj[(rowS + lane) * LDP + PC_DT + grp * 4 + w];
.LBB0_334:
	s_andn2_saveexec_b64 s[8:9], s[8:9]
	s_lshl_b32 s10, s3, 8
	v_lshl_or_b32 v114, v111, 3, s10
	s_or_b64 exec, exec, s[8:9]
	v_ashrrev_i32_e32 v116, 6, v139
	v_ashrrev_i32_e32 v117, 31, v116
	v_lshl_add_u64 v[0:1], s[66:67], 0, v[116:117]
	v_mov_b64_e32 v[2:3], s[78:79]
	v_mad_u64_u32 v[2:3], s[8:9], v0, s77, v[2:3]
	v_mov_b32_e32 v0, v3
	v_mad_u64_u32 v[0:1], s[8:9], v1, s77, v[0:1]
	v_mov_b32_e32 v3, v0
	v_mov_b32_e32 v115, v11
	v_lshl_add_u64 v[0:1], v[114:115], 1, v[2:3]
	v_lshl_add_u64 v[4:5], v[0:1], 0, s[92:93]
	global_load_dwordx4 v[0:3], v[4:5], off nt
	v_lshl_add_u64 v[12:13], v[4:5], 0, s[84:85]
	global_load_dwordx4 v[4:7], v[12:13], off nt
	v_lshl_add_u64 v[16:17], v[12:13], 0, s[84:85]
	global_load_dwordx4 v[12:15], v[16:17], off nt
	v_lshl_add_u64 v[20:21], v[16:17], 0, s[84:85]
	global_load_dwordx4 v[16:19], v[20:21], off nt
	v_lshl_add_u64 v[24:25], v[20:21], 0, s[84:85]
	global_load_dwordx4 v[20:23], v[24:25], off nt
	v_lshl_add_u64 v[28:29], v[24:25], 0, s[84:85]
	global_load_dwordx4 v[24:27], v[28:29], off nt
	v_lshl_add_u64 v[32:33], v[28:29], 0, s[84:85]
	global_load_dwordx4 v[28:31], v[32:33], off nt
	v_lshl_add_u64 v[32:33], v[32:33], 0, s[84:85]
	global_load_dwordx4 v[32:35], v[32:33], off nt
	v_cmp_gt_i32_e64 s[8:9], 4, v116
	v_cmp_lt_i32_e32 vcc, 3, v116
	s_and_saveexec_b64 s[10:11], vcc
	s_xor_b64 s[10:11], exec, s[10:11]
	s_lshl_b32 s12, s3, 2
	s_or_saveexec_b64 s[10:11], s[10:11]
	v_mov_b32_e32 v140, 0
	v_mov_b32_e32 v36, s12
	v_mov_b32_e32 v142, 0
	s_xor_b64 exec, exec, s[10:11]
	s_cbranch_execz .LBB0_340
	v_or_b32_e32 v38, s66, v111
	v_mov_b64_e32 v[36:37], s[78:79]
	s_mul_i32 s14, s67, 0x6200
	v_mad_u64_u32 v[36:37], s[12:13], v38, s77, v[36:37]
	v_add_u32_e32 v37, s14, v37
	s_lshl_b32 s64, s3, 3
	v_lshl_add_u64 v[36:37], v[36:37], 0, s[64:65]
	v_lshl_add_u64 v[36:37], v[116:117], 1, v[36:37]
	v_add_co_u32_e32 v36, vcc, 0x6000, v36
	s_lshl_b32 s3, s3, 2
	s_nop 0
	v_addc_co_u32_e32 v37, vcc, 0, v37, vcc
	global_load_ushort v142, v[36:37], off
	v_mov_b32_e32 v36, s3

; #define LAS __attribute__((address_space(3)))
; #define LAUNDER_PTR(p) do {} while (0)
; #define LAUNDER_PTR(p) asm volatile("" : "+v"(p))
; __device__ __forceinline__ void ssd_pass1(const RecurBufs& rb, const float* conv_w, const float* conv_b, const float* dt_bias, const float* a_log, float* conv_out_l, int u, int tid, LAS unsigned char* lds) {
;     ...
;         for (int i = 0; i < 8; ++i) *(LAS v4u*)(T + (rr + 8 * i) * PR + ch16 * 16) = raw[i];
;         if (ch + 1 < NCH) { const bf16* gp = rb.proj + (row0 + RC + rr) * LDP + PC_XBC + gcol;
; #pragma unroll
;             for (int i = 0; i < 8; ++i) { LAUNDER_PTR(gp); raw[i] = *(const v4u*)gp; gp += 8 * (size_t)LDP; } }
.LBB0_348:
	s_or_b64 exec, exec, s[70:71]
	s_cmp_eq_u32 s3, 7
	s_waitcnt vmcnt(0) lgkmcnt(0)
	ds_write_b128 v218, v[0:3]
	ds_write_b128 v218, v[4:7] offset:8320
	ds_write_b128 v218, v[12:15] offset:16640
	ds_write_b128 v218, v[16:19] offset:24960
	ds_write_b128 v218, v[20:23] offset:33280
	ds_write_b128 v218, v[24:27] offset:41600
	ds_write_b128 v218, v[28:31] offset:49920
	ds_write_b128 v218, v[32:35] offset:58240
	s_cbranch_scc1 .LBB0_350
	v_lshl_add_u64 v[0:1], v[124:125], 0, s[68:69]
	v_mov_b64_e32 v[2:3], s[78:79]
	v_mad_u64_u32 v[2:3], s[50:51], v0, s77, v[2:3]
	v_mov_b32_e32 v0, v3
	v_mad_u64_u32 v[0:1], s[50:51], v1, s77, v[0:1]
	v_mov_b32_e32 v3, v0
	v_lshl_add_u64 v[0:1], v[114:115], 1, v[2:3]
	v_lshl_add_u64 v[4:5], v[0:1], 0, s[92:93]
	global_load_dwordx4 v[0:3], v[4:5], off nt
	v_lshl_add_u64 v[12:13], v[4:5], 0, s[84:85]
	global_load_dwordx4 v[4:7], v[12:13], off nt
	v_lshl_add_u64 v[16:17], v[12:13], 0, s[84:85]
	global_load_dwordx4 v[12:15], v[16:17], off nt
	v_lshl_add_u64 v[20:21], v[16:17], 0, s[84:85]
	global_load_dwordx4 v[16:19], v[20:21], off nt
	v_lshl_add_u64 v[24:25], v[20:21], 0, s[84:85]
	global_load_dwordx4 v[20:23], v[24:25], off nt
	v_lshl_add_u64 v[28:29], v[24:25], 0, s[84:85]
	global_load_dwordx4 v[24:27], v[28:29], off nt
	v_lshl_add_u64 v[32:33], v[28:29], 0, s[84:85]
	global_load_dwordx4 v[28:31], v[32:33], off nt
	v_lshl_add_u64 v[32:33], v[32:33], 0, s[84:85]
	global_load_dwordx4 v[32:35], v[32:33], off nt

; #define LAS __attribute__((address_space(3)))
; __device__ __forceinline__ void hgrn_pass1(const RecurBufs& rb, const float* lbs_l, int u, int tid, LAS unsigned char* lds) {
;     const int b = u >> 5, h = (u >> 2) & 7, seg = u & 3, lane = tid & 63, w = tid >> 6;
;     const int d = tid & 127, jq = tid >> 7;
;     LAS unsigned char* Qt = lds + HG_QT; LAS unsigned char* Kt = lds + HG_KT; LAS unsigned char* V = lds + HG_V; LAS float* part = (LAS float*)(lds + HG_PART); LAS float* vec = (LAS float*)(lds + HG_VEC1);
;     const float lb = lbs_l[h * 128 + d];
;     f32x4 S[8];
; #pragma unroll
;     for (int et = 0; et < 8; ++et) S[et] = (f32x4){0.f, 0.f, 0.f, 0.f};
;     float dprod = 1.f;
;     const int sr = tid >> 4, sc16 = tid & 15;
;     v4u pre[6];
;     {   const bf16* gq = rb.proj + ((size_t)b * SEQ + seg * SEGLEN + sr) * LDP + PC_Q + h * 128 + sc16 * 8;
;         pre[0] = *(const v4u*)gq; pre[1] = *(const v4u*)(gq + 32 * (size_t)LDP); pre[2] = *(const v4u*)(gq + PC_F); pre[3] = *(const v4u*)(gq + 32 * (size_t)LDP + PC_F);
;         pre[4] = *(const v4u*)(gq + PC_I); pre[5] = *(const v4u*)(gq + 32 * (size_t)LDP + PC_I); }
.LBB0_391:
	s_bfe_u32 s4, s16, 0x30002
	v_mov_b32_e32 v97, v138
	s_lshl_b32 s17, s4, 7
	v_and_b32_e32 v92, 0x7f, v97
	s_and_b32 s3, s18, 3
	s_ashr_i32 s2, s16, 5
	v_or_b32_e32 v0, s17, v92
	s_and_b32 s19, s16, 3
	s_lshl_b32 s14, s3, 3
	s_lshl_b32 s23, s3, 9
	s_ashr_i32 s3, s2, 31
	v_lshlrev_b32_e32 v10, 2, v0
	s_lshl_b32 s5, s19, 9
	s_lshl_b32 s9, s2, 8
	v_ashrrev_i32_e32 v2, 4, v97
	s_lshl_b64 s[2:3], s[2:3], 11
	v_lshl_add_u64 v[0:1], s[96:97], 0, v[10:11]
	s_lshl_b32 s8, s4, 5
	s_lshl_b32 s64, s4, 8
	s_or_b32 s4, s2, s5
	s_mov_b32 s5, s3
	v_ashrrev_i32_e32 v3, 31, v2
	global_load_dword v93, v[0:1], off
	v_mov_b64_e32 v[0:1], s[78:79]
	v_lshl_add_u64 v[4:5], s[4:5], 0, v[2:3]
	v_mad_u64_u32 v[94:95], s[4:5], v4, s77, v[0:1]
	v_and_b32_e32 v12, 15, v97
	v_mad_i32_i24 v95, v5, s77, v95
	v_lshlrev_b32_e32 v10, 4, v12
	v_lshl_add_u64 v[0:1], v[94:95], 0, s[64:65]
	v_lshl_add_u64 v[0:1], v[0:1], 0, v[10:11]
	s_mov_b32 s4, 0xc4000
	v_add_co_u32_e32 v4, vcc, s4, v0
	s_movk_i32 s4, 0x1000
	s_nop 0
	v_addc_co_u32_e32 v5, vcc, 0, v1, vcc
	v_add_co_u32_e32 v6, vcc, s4, v0
	s_mov_b32 s4, 0xc5000
	s_nop 0
	v_addc_co_u32_e32 v7, vcc, 0, v1, vcc
	v_add_co_u32_e32 v8, vcc, s4, v0
	global_load_dwordx4 v[36:39], v[0:1], off nt
	s_nop 0
	v_addc_co_u32_e32 v9, vcc, 0, v1, vcc
	global_load_dwordx4 v[44:47], v[4:5], off nt
	global_load_dwordx4 v[40:43], v[0:1], off offset:2048 nt
	global_load_dwordx4 v[48:51], v[4:5], off offset:2048 nt
	global_load_dwordx4 v[52:55], v[6:7], off nt
	global_load_dwordx4 v[56:59], v[8:9], off nt
	v_lshlrev_b32_e32 v8, 2, v97
	v_ashrrev_i32_e32 v1, 2, v97
	s_or_b32 s28, s9, s8
	s_movk_i32 s15, 0x110
	v_lshrrev_b32_e32 v5, 1, v97
	v_bfe_u32 v6, v97, 2, 2
	v_mul_lo_u32 v7, v2, s15
	v_lshlrev_b32_e32 v112, 1, v92
	v_and_b32_e32 v1, -16, v1
	v_and_b32_e32 v9, 12, v8
	s_or_b32 s14, s28, s14
	v_mov_b32_e32 v101, 1.0
	v_ashrrev_i32_e32 v0, 7, v97
	v_and_or_b32 v5, v5, 24, v6
	v_add_u32_e32 v6, 0, v7
	v_add_u32_e32 v100, 0, v112
	v_lshl_add_u32 v7, v1, 2, 0
	v_or_b32_e32 v1, v9, v1
	s_mul_hi_i32 s29, s14, 0x600
	s_mul_i32 s50, s14, 0x600
	s_movk_i32 s14, 0x1100
	s_or_b32 s2, s2, s23
	v_lshlrev_b32_e32 v96, 3, v12
	v_cmp_lt_i32_e64 s[10:11], 0, v0
	v_cmp_lt_i32_e64 s[12:13], 1, v0
	v_cmp_lt_i32_e64 s[8:9], 2, v0
	v_mul_u32_u24_e32 v13, 0x110, v5
	v_mad_u32_u24 v5, v5, s15, 0
	v_lshl_add_u32 v106, v12, 2, v7
	v_lshl_add_u32 v12, v1, 1, 0
	v_mad_u64_u32 v[98:99], s[14:15], v0, s14, v[100:101]
	v_lshl_add_u64 v[0:1], s[2:3], 0, v[2:3]
	v_mov_b64_e32 v[2:3], s[64:65]
	s_movk_i32 s4, 0x80
	s_movk_i32 s6, 0x7f
	v_and_b32_e32 v4, 48, v97
	v_lshlrev_b32_e32 v9, 1, v9
	v_mad_u64_u32 v[2:3], s[2:3], v0, s77, v[2:3]
	v_mov_b32_e32 v0, 0
	s_mov_b32 s22, 7
	v_cmp_gt_u32_e64 s[4:5], s4, v97
	v_cmp_lt_u32_e64 s[6:7], s6, v97
	v_add_u32_e32 v109, 0, v8
	v_lshl_or_b32 v102, v92, 2, s50
	v_mov_b32_e32 v103, s29
	v_mad_i32_i24 v105, v1, s77, v3
	v_or_b32_e32 v104, v2, v10
	v_add_u32_e32 v108, v6, v10
	v_add_u32_e32 v107, v7, v4
	v_add_u32_e32 v99, v12, v13
	v_add_u32_e32 v9, v5, v9
	s_waitcnt vmcnt(0) lgkmcnt(0)
	v_sub_f32_e32 v110, 1.0, v93
	v_mov_b32_e32 v1, v0
	v_mov_b32_e32 v2, v0
	v_mov_b32_e32 v3, v0
	v_mov_b32_e32 v4, v0
	v_mov_b32_e32 v5, v0
	v_mov_b32_e32 v6, v0
	v_mov_b32_e32 v7, v0
	v_mov_b32_e32 v12, v0
	v_mov_b32_e32 v13, v0
	v_mov_b32_e32 v14, v0
	v_mov_b32_e32 v15, v0
	v_mov_b32_e32 v16, v0
	v_mov_b32_e32 v17, v0
	v_mov_b32_e32 v18, v0
	v_mov_b32_e32 v19, v0
	v_mov_b32_e32 v20, v0
	v_mov_b32_e32 v21, v0
	v_mov_b32_e32 v22, v0
	v_mov_b32_e32 v23, v0
	v_mov_b32_e32 v24, v0
	v_mov_b32_e32 v25, v0
	v_mov_b32_e32 v26, v0
	v_mov_b32_e32 v27, v0
	v_mov_b32_e32 v28, v0
	v_mov_b32_e32 v29, v0
	v_mov_b32_e32 v30, v0
	v_mov_b32_e32 v31, v0
	v_mov_b32_e32 v32, v0
	v_mov_b32_e32 v33, v0
	v_mov_b32_e32 v34, v0
	v_mov_b32_e32 v35, v0
	s_branch .LBB0_393

; __device__ __forceinline__ float bf2f(bf16 v) { return __uint_as_float(((unsigned)v) << 16); }
; __device__ __forceinline__ float sigmoidf_(float x) { return frcp_(1.0f + __expf(-x)); }
; __device__ __forceinline__ float siluf_(float x) { return x * frcp_(1.0f + __expf(-x)); }
; #define LAS __attribute__((address_space(3)))
; __device__ __forceinline__ void sync_threads() { __syncthreads(); }
; __device__ __forceinline__ void hgrn_pass1(const RecurBufs& rb, const float* lbs_l, int u, int tid, LAS unsigned char* lds) {
;     ...
;         const size_t row0 = (size_t)b * SEQ + seg * SEGLEN + ch * RC;
;         bf16* gq = rb.proj + (row0 + sr) * LDP + PC_Q + h * 128 + sc16 * 8;
;         *(LAS v4u*)(Qt + sr * PQ + sc16 * 16) = pre[0]; *(LAS v4u*)(Qt + (sr + 32) * PQ + sc16 * 16) = pre[1];
;         *(LAS v4u*)(Kt + sr * PQ + sc16 * 16) = pre[2]; *(LAS v4u*)(Kt + (sr + 32) * PQ + sc16 * 16) = pre[3];
;         *(LAS v4u*)(V + sr * PQ + sc16 * 16) = pre[4]; *(LAS v4u*)(V + (sr + 32) * PQ + sc16 * 16) = pre[5];
;         if (ch + 1 < NCH) { const bf16* gn = gq + RC * (size_t)LDP;
;             pre[0] = *(const v4u*)gn; pre[1] = *(const v4u*)(gn + 32 * (size_t)LDP); pre[2] = *(const v4u*)(gn + PC_F); pre[3] = *(const v4u*)(gn + 32 * (size_t)LDP + PC_F);
;             pre[4] = *(const v4u*)(gn + PC_I); pre[5] = *(const v4u*)(gn + 32 * (size_t)LDP + PC_I); }
;         sync_threads();
;         float qq[16], kk[16], lg[16];
; #pragma unroll
;         for (int j = 0; j < 16; ++j) { const float q = bf2f(*(const LAS bf16*)(Qt + (16 * jq + j) * PQ + d * 2)), f = bf2f(*(const LAS bf16*)(Kt + (16 * jq + j) * PQ + d * 2));
;             const float fg = lb + (1.f - lb) * sigmoidf_(f);
;             qq[j] = siluf_(q) * 0.08838834764831845f; kk[j] = 1.f - fg; lg[j] = __logf(fg); }
.LBB0_393:
	v_lshl_add_u64 v[60:61], s[72:73], 0, v[104:105]
	s_waitcnt vmcnt(0)
	ds_write_b128 v108, v[36:39]
	ds_write_b128 v108, v[44:47] offset:8704
	ds_write_b128 v108, v[40:43] offset:17408
	ds_write_b128 v108, v[48:51] offset:26112
	ds_write_b128 v108, v[52:55] offset:34816
	ds_write_b128 v108, v[56:59] offset:43520
	v_add_co_u32_e32 v40, vcc, s38, v60
	s_nop 1
	v_addc_co_u32_e32 v41, vcc, 0, v61, vcc
	v_add_co_u32_e32 v48, vcc, s39, v60
	s_nop 1
	v_addc_co_u32_e32 v49, vcc, 0, v61, vcc
	v_add_co_u32_e32 v52, vcc, s55, v60
	global_load_dwordx4 v[36:39], v[40:41], off nt
	s_nop 0
	global_load_dwordx4 v[40:43], v[40:41], off offset:2048 nt
	s_nop 0
	global_load_dwordx4 v[44:47], v[48:49], off nt
	s_nop 0
	global_load_dwordx4 v[48:51], v[48:49], off offset:2048 nt
	v_addc_co_u32_e32 v53, vcc, 0, v61, vcc
	v_add_co_u32_e32 v56, vcc, s80, v60
	s_nop 1
	v_addc_co_u32_e32 v57, vcc, 0, v61, vcc
	global_load_dwordx4 v[52:55], v[52:53], off nt
	s_nop 0
	global_load_dwordx4 v[56:59], v[56:57], off nt
	s_waitcnt lgkmcnt(0)
	s_barrier
	ds_read_u16 v10, v98 offset:17408
	ds_read_u16 v62, v98 offset:17680
	ds_read_u16 v64, v98 offset:17952
	ds_read_u16 v66, v98 offset:18224
	ds_read_u16 v68, v98 offset:18496
	ds_read_u16 v71, v98 offset:18768
	ds_read_u16 v73, v98 offset:19040
	ds_read_u16 v76, v98 offset:19312
	s_waitcnt lgkmcnt(0)
	v_lshlrev_b32_e32 v10, 16, v10
	v_mul_f32_e32 v10, 0xbfb8aa3b, v10
	v_exp_f32_e32 v10, v10
	ds_read_u16 v63, v98
	ds_read_u16 v65, v98 offset:272
	ds_read_u16 v67, v98 offset:544
	ds_read_u16 v70, v98 offset:816
	ds_read_u16 v72, v98 offset:1088
	ds_read_u16 v74, v98 offset:1360
	ds_read_u16 v75, v98 offset:1632
	ds_read_u16 v77, v98 offset:1904
	s_waitcnt lgkmcnt(0)
	v_lshlrev_b32_e32 v63, 16, v63
	v_mul_f32_e32 v69, 0xbfb8aa3b, v63
	v_add_f32_e32 v10, 1.0, v10
	v_rcp_f32_e32 v10, v10
	v_exp_f32_e32 v69, v69
	v_lshlrev_b32_e32 v62, 16, v62
	v_mul_f32_e32 v62, 0xbfb8aa3b, v62
	v_fma_f32 v10, v110, v10, v93
	v_cmp_gt_f32_e32 vcc, s33, v10
	v_add_f32_e32 v69, 1.0, v69
	v_rcp_f32_e32 v69, v69
	v_cndmask_b32_e64 v78, 0, 32, vcc
	v_ldexp_f32 v78, v10, v78
	v_log_f32_e32 v78, v78
	v_exp_f32_e32 v62, v62
	v_mul_f32_e32 v63, v69, v63
	v_lshlrev_b32_e32 v65, 16, v65
	v_mul_f32_e32 v69, 0x3f317217, v78
	v_fma_f32 v69, v78, s74, -v69
	v_add_f32_e32 v62, 1.0, v62
	v_fmac_f32_e32 v69, 0x3377d1cf, v78
	v_rcp_f32_e32 v62, v62
	v_fmac_f32_e32 v69, 0x3f317217, v78
	v_cmp_lt_f32_e64 s[14:15], |v78|, s81
	v_cndmask_b32_e32 v79, 0, v186, vcc
	v_fma_f32 v62, v110, v62, v93
	v_cndmask_b32_e64 v69, v78, v69, s[14:15]
	v_mul_f32_e32 v78, 0xbfb8aa3b, v65
	v_exp_f32_e32 v78, v78
	v_cmp_gt_f32_e32 vcc, s33, v62
	v_sub_f32_e32 v69, v69, v79
	v_lshlrev_b32_e32 v64, 16, v64
	v_cndmask_b32_e64 v79, 0, 32, vcc
	v_add_f32_e32 v78, 1.0, v78
	v_ldexp_f32 v79, v62, v79
	v_rcp_f32_e32 v78, v78
	v_log_f32_e32 v79, v79
	v_mul_f32_e32 v64, 0xbfb8aa3b, v64
	v_exp_f32_e32 v64, v64
	v_mul_f32_e32 v65, v78, v65
	v_mul_f32_e32 v78, 0x3f317217, v79
	v_fma_f32 v78, v79, s74, -v78
	v_add_f32_e32 v64, 1.0, v64
	v_fmac_f32_e32 v78, 0x3377d1cf, v79
	v_rcp_f32_e32 v64, v64
	v_fmac_f32_e32 v78, 0x3f317217, v79
	v_cmp_lt_f32_e64 s[14:15], |v79|, s81
	v_lshlrev_b32_e32 v67, 16, v67
	v_fma_f32 v64, v110, v64, v93
	v_cndmask_b32_e64 v78, v79, v78, s[14:15]
	v_mul_f32_e32 v79, 0xbfb8aa3b, v67
	v_exp_f32_e32 v79, v79
	v_cndmask_b32_e32 v80, 0, v186, vcc
	v_cmp_gt_f32_e32 vcc, s33, v64
	v_sub_f32_e32 v78, v78, v80
	v_add_f32_e32 v79, 1.0, v79
	v_cndmask_b32_e64 v80, 0, 32, vcc
	v_ldexp_f32 v80, v64, v80
	v_lshlrev_b32_e32 v66, 16, v66
	v_rcp_f32_e32 v79, v79
	v_log_f32_e32 v80, v80
	v_mul_f32_e32 v66, 0xbfb8aa3b, v66
	v_exp_f32_e32 v66, v66
	v_mul_f32_e32 v67, v79, v67
	v_mul_f32_e32 v79, 0x3f317217, v80
	v_fma_f32 v79, v80, s74, -v79
	v_add_f32_e32 v66, 1.0, v66
	v_fmac_f32_e32 v79, 0x3377d1cf, v80
	v_rcp_f32_e32 v66, v66
	v_fmac_f32_e32 v79, 0x3f317217, v80
	v_cmp_lt_f32_e64 s[14:15], |v80|, s81
	v_lshlrev_b32_e32 v70, 16, v70
	v_fma_f32 v66, v110, v66, v93
	v_cndmask_b32_e64 v79, v80, v79, s[14:15]
	v_mul_f32_e32 v80, 0xbfb8aa3b, v70
	v_exp_f32_e32 v80, v80
	v_cndmask_b32_e32 v81, 0, v186, vcc
	v_cmp_gt_f32_e32 vcc, s33, v66
	v_sub_f32_e32 v79, v79, v81
	v_add_f32_e32 v80, 1.0, v80
	v_cndmask_b32_e64 v81, 0, 32, vcc
	v_ldexp_f32 v81, v66, v81
	v_lshlrev_b32_e32 v68, 16, v68
	v_rcp_f32_e32 v80, v80
	v_log_f32_e32 v81, v81
	v_mul_f32_e32 v68, 0xbfb8aa3b, v68
	v_exp_f32_e32 v68, v68
	v_mul_f32_e32 v70, v80, v70
	v_mul_f32_e32 v80, 0x3f317217, v81
	v_fma_f32 v80, v81, s74, -v80
	v_add_f32_e32 v68, 1.0, v68
	v_fmac_f32_e32 v80, 0x3377d1cf, v81
	v_rcp_f32_e32 v68, v68
	v_fmac_f32_e32 v80, 0x3f317217, v81
	v_cmp_lt_f32_e64 s[14:15], |v81|, s81
	v_lshlrev_b32_e32 v72, 16, v72
	v_fma_f32 v68, v110, v68, v93
	v_cndmask_b32_e64 v80, v81, v80, s[14:15]
	v_mul_f32_e32 v81, 0xbfb8aa3b, v72
	v_exp_f32_e32 v81, v81
	v_cndmask_b32_e32 v82, 0, v186, vcc
	v_cmp_gt_f32_e32 vcc, s33, v68
	v_sub_f32_e32 v80, v80, v82
	v_add_f32_e32 v81, 1.0, v81
	v_cndmask_b32_e64 v82, 0, 32, vcc
	v_ldexp_f32 v82, v68, v82
	v_lshlrev_b32_e32 v71, 16, v71
	v_rcp_f32_e32 v81, v81
	v_log_f32_e32 v82, v82
	v_mul_f32_e32 v71, 0xbfb8aa3b, v71
	v_exp_f32_e32 v71, v71
	v_mul_f32_e32 v72, v81, v72
	v_mul_f32_e32 v81, 0x3f317217, v82
	v_fma_f32 v81, v82, s74, -v81
	v_add_f32_e32 v71, 1.0, v71
	v_fmac_f32_e32 v81, 0x3377d1cf, v82
	v_rcp_f32_e32 v71, v71
	v_fmac_f32_e32 v81, 0x3f317217, v82
	v_cmp_lt_f32_e64 s[14:15], |v82|, s81
	v_lshlrev_b32_e32 v74, 16, v74
	v_fma_f32 v71, v110, v71, v93
	v_cndmask_b32_e64 v81, v82, v81, s[14:15]
	v_mul_f32_e32 v82, 0xbfb8aa3b, v74
	v_exp_f32_e32 v82, v82
	v_cndmask_b32_e32 v83, 0, v186, vcc
; __device__ __forceinline__ float bf2f(bf16 v) { return __uint_as_float(((unsigned)v) << 16); }
; __device__ __forceinline__ float sigmoidf_(float x) { return frcp_(1.0f + __expf(-x)); }
; __device__ __forceinline__ float siluf_(float x) { return x * frcp_(1.0f + __expf(-x)); }
; #define LAS __attribute__((address_space(3)))
; __device__ __forceinline__ void hgrn_pass1(const RecurBufs& rb, const float* lbs_l, int u, int tid, LAS unsigned char* lds) {
;     ...
;         for (int j = 0; j < 16; ++j) { const float q = bf2f(*(const LAS bf16*)(Qt + (16 * jq + j) * PQ + d * 2)), f = bf2f(*(const LAS bf16*)(Kt + (16 * jq + j) * PQ + d * 2));
;             const float fg = lb + (1.f - lb) * sigmoidf_(f);
;             qq[j] = siluf_(q) * 0.08838834764831845f; kk[j] = 1.f - fg; lg[j] = __logf(fg); }
	v_cmp_gt_f32_e32 vcc, s33, v71
	v_sub_f32_e32 v81, v81, v83
	v_add_f32_e32 v82, 1.0, v82
	v_cndmask_b32_e64 v83, 0, 32, vcc
	v_ldexp_f32 v83, v71, v83
	v_lshlrev_b32_e32 v73, 16, v73
	v_rcp_f32_e32 v82, v82
	v_log_f32_e32 v83, v83
	v_mul_f32_e32 v73, 0xbfb8aa3b, v73
	v_exp_f32_e32 v73, v73
	v_mul_f32_e32 v74, v82, v74
	v_mul_f32_e32 v82, 0x3f317217, v83
	v_fma_f32 v82, v83, s74, -v82
	v_add_f32_e32 v73, 1.0, v73
	v_fmac_f32_e32 v82, 0x3377d1cf, v83
	v_rcp_f32_e32 v73, v73
	v_fmac_f32_e32 v82, 0x3f317217, v83
	v_cmp_lt_f32_e64 s[14:15], |v83|, s81
	v_lshlrev_b32_e32 v75, 16, v75
	v_fma_f32 v73, v110, v73, v93
	v_cndmask_b32_e64 v82, v83, v82, s[14:15]
	v_mul_f32_e32 v83, 0xbfb8aa3b, v75
	v_exp_f32_e32 v83, v83
	v_cndmask_b32_e32 v84, 0, v186, vcc
	v_cmp_gt_f32_e32 vcc, s33, v73
	v_sub_f32_e32 v82, v82, v84
	v_add_f32_e32 v83, 1.0, v83
	v_cndmask_b32_e64 v84, 0, 32, vcc
	v_ldexp_f32 v84, v73, v84
	v_lshlrev_b32_e32 v76, 16, v76
	v_rcp_f32_e32 v83, v83
	v_log_f32_e32 v84, v84
	v_mul_f32_e32 v76, 0xbfb8aa3b, v76
	v_exp_f32_e32 v76, v76
	v_mul_f32_e32 v75, v83, v75
	v_mul_f32_e32 v83, 0x3f317217, v84
	v_fma_f32 v83, v84, s74, -v83
	v_add_f32_e32 v76, 1.0, v76
	v_fmac_f32_e32 v83, 0x3377d1cf, v84
	v_rcp_f32_e32 v76, v76
	v_fmac_f32_e32 v83, 0x3f317217, v84
	v_cmp_lt_f32_e64 s[14:15], |v84|, s81
	v_lshlrev_b32_e32 v77, 16, v77
	v_fma_f32 v76, v110, v76, v93
	v_cndmask_b32_e64 v83, v84, v83, s[14:15]
	v_mul_f32_e32 v84, 0xbfb8aa3b, v77
	v_exp_f32_e32 v84, v84
	v_cndmask_b32_e32 v85, 0, v186, vcc
	v_cmp_gt_f32_e32 vcc, s33, v76
	v_sub_f32_e32 v83, v83, v85
	v_add_f32_e32 v84, 1.0, v84
	v_cndmask_b32_e64 v85, 0, 32, vcc
	v_ldexp_f32 v85, v76, v85
	v_rcp_f32_e32 v84, v84
	v_log_f32_e32 v85, v85
	v_cndmask_b32_e32 v122, 0, v186, vcc
	v_mul_f32_e32 v63, 0x3db504f3, v63
	v_mul_f32_e32 v77, v84, v77
	v_mul_f32_e32 v84, 0x3f317217, v85
	v_fma_f32 v84, v85, s74, -v84
	v_fmac_f32_e32 v84, 0x3377d1cf, v85
	v_fmac_f32_e32 v84, 0x3f317217, v85
	v_cmp_lt_f32_e64 s[14:15], |v85|, s81
	v_sub_f32_e32 v10, 1.0, v10
	v_mul_f32_e32 v65, 0x3db504f3, v65
	v_cndmask_b32_e64 v84, v85, v84, s[14:15]
	ds_read_u16 v85, v98 offset:19584
	ds_read_u16 v86, v98 offset:19856
	ds_read_u16 v87, v98 offset:20128
	ds_read_u16 v88, v98 offset:20400
	ds_read_u16 v89, v98 offset:20672
	ds_read_u16 v90, v98 offset:20944
	ds_read_u16 v91, v98 offset:21216
	ds_read_u16 v111, v98 offset:21488
	s_waitcnt lgkmcnt(0)
	v_lshlrev_b32_e32 v85, 16, v85
	v_mul_f32_e32 v85, 0xbfb8aa3b, v85
	v_exp_f32_e32 v85, v85
	ds_read_u16 v113, v98 offset:2176
	ds_read_u16 v114, v98 offset:2448
	ds_read_u16 v115, v98 offset:2720
	ds_read_u16 v116, v98 offset:2992
	ds_read_u16 v117, v98 offset:3264
	ds_read_u16 v118, v98 offset:3536
	ds_read_u16 v119, v98 offset:3808
	ds_read_u16 v120, v98 offset:4080
	s_waitcnt lgkmcnt(0)
	v_lshlrev_b32_e32 v113, 16, v113
	v_mul_f32_e32 v121, 0xbfb8aa3b, v113
	v_add_f32_e32 v85, 1.0, v85
	v_rcp_f32_e32 v85, v85
	v_exp_f32_e32 v121, v121
	v_sub_f32_e32 v84, v84, v122
	v_lshlrev_b32_e32 v86, 16, v86
	v_fma_f32 v85, v110, v85, v93
	v_cmp_gt_f32_e32 vcc, s33, v85
	v_add_f32_e32 v121, 1.0, v121
	v_rcp_f32_e32 v121, v121
	v_cndmask_b32_e64 v122, 0, 32, vcc
	v_ldexp_f32 v122, v85, v122
	v_log_f32_e32 v122, v122
	v_mul_f32_e32 v86, 0xbfb8aa3b, v86
	v_exp_f32_e32 v86, v86
	v_mul_f32_e32 v113, v121, v113
	v_mul_f32_e32 v121, 0x3f317217, v122
	v_fma_f32 v121, v122, s74, -v121
	v_add_f32_e32 v86, 1.0, v86
	v_fmac_f32_e32 v121, 0x3377d1cf, v122
	v_rcp_f32_e32 v86, v86
	v_fmac_f32_e32 v121, 0x3f317217, v122
	v_cmp_lt_f32_e64 s[14:15], |v122|, s81
	v_lshlrev_b32_e32 v114, 16, v114
	v_fma_f32 v86, v110, v86, v93
	v_cndmask_b32_e64 v121, v122, v121, s[14:15]
	v_mul_f32_e32 v122, 0xbfb8aa3b, v114
	v_exp_f32_e32 v122, v122
	v_cndmask_b32_e32 v123, 0, v186, vcc
	v_cmp_gt_f32_e32 vcc, s33, v86
	v_sub_f32_e32 v121, v121, v123
	v_add_f32_e32 v122, 1.0, v122
	v_cndmask_b32_e64 v123, 0, 32, vcc
	v_ldexp_f32 v123, v86, v123
	v_lshlrev_b32_e32 v87, 16, v87
	v_rcp_f32_e32 v122, v122
	v_log_f32_e32 v123, v123
	v_mul_f32_e32 v87, 0xbfb8aa3b, v87
	v_exp_f32_e32 v87, v87
	v_mul_f32_e32 v114, v122, v114
	v_mul_f32_e32 v122, 0x3f317217, v123
	v_fma_f32 v122, v123, s74, -v122
	v_add_f32_e32 v87, 1.0, v87
	v_fmac_f32_e32 v122, 0x3377d1cf, v123
	v_rcp_f32_e32 v87, v87
	v_fmac_f32_e32 v122, 0x3f317217, v123
	v_cmp_lt_f32_e64 s[14:15], |v123|, s81
	v_lshlrev_b32_e32 v115, 16, v115
	v_fma_f32 v87, v110, v87, v93
	v_cndmask_b32_e64 v122, v123, v122, s[14:15]
	v_mul_f32_e32 v123, 0xbfb8aa3b, v115
	v_exp_f32_e32 v123, v123
	v_cndmask_b32_e32 v124, 0, v186, vcc
	v_cmp_gt_f32_e32 vcc, s33, v87
	v_sub_f32_e32 v122, v122, v124
	v_add_f32_e32 v123, 1.0, v123
	v_cndmask_b32_e64 v124, 0, 32, vcc
	v_ldexp_f32 v124, v87, v124
	v_lshlrev_b32_e32 v88, 16, v88
	v_rcp_f32_e32 v123, v123
	v_log_f32_e32 v124, v124
	v_mul_f32_e32 v88, 0xbfb8aa3b, v88
	v_exp_f32_e32 v88, v88
	v_mul_f32_e32 v115, v123, v115
	v_mul_f32_e32 v123, 0x3f317217, v124
	v_fma_f32 v123, v124, s74, -v123
	v_add_f32_e32 v88, 1.0, v88
	v_fmac_f32_e32 v123, 0x3377d1cf, v124
	v_rcp_f32_e32 v88, v88
	v_fmac_f32_e32 v123, 0x3f317217, v124
	v_cmp_lt_f32_e64 s[14:15], |v124|, s81
	v_lshlrev_b32_e32 v116, 16, v116
	v_fma_f32 v88, v110, v88, v93
	v_cndmask_b32_e64 v123, v124, v123, s[14:15]
	v_mul_f32_e32 v124, 0xbfb8aa3b, v116
	v_exp_f32_e32 v124, v124
	v_cndmask_b32_e32 v125, 0, v186, vcc
	v_cmp_gt_f32_e32 vcc, s33, v88
	v_sub_f32_e32 v123, v123, v125
	v_add_f32_e32 v124, 1.0, v124
	v_cndmask_b32_e64 v125, 0, 32, vcc
	v_ldexp_f32 v125, v88, v125
	v_lshlrev_b32_e32 v89, 16, v89
	v_rcp_f32_e32 v124, v124
	v_log_f32_e32 v125, v125
	v_mul_f32_e32 v89, 0xbfb8aa3b, v89
; __device__ __forceinline__ float bf2f(bf16 v) { return __uint_as_float(((unsigned)v) << 16); }
; __device__ __forceinline__ float sigmoidf_(float x) { return frcp_(1.0f + __expf(-x)); }
; __device__ __forceinline__ float siluf_(float x) { return x * frcp_(1.0f + __expf(-x)); }
; #define LAS __attribute__((address_space(3)))
; __device__ __forceinline__ void sync_threads() { __syncthreads(); }
; __device__ __forceinline__ void hgrn_pass1(const RecurBufs& rb, const float* lbs_l, int u, int tid, LAS unsigned char* lds) {
;     ...
;         for (int j = 0; j < 16; ++j) { const float q = bf2f(*(const LAS bf16*)(Qt + (16 * jq + j) * PQ + d * 2)), f = bf2f(*(const LAS bf16*)(Kt + (16 * jq + j) * PQ + d * 2));
;             const float fg = lb + (1.f - lb) * sigmoidf_(f);
;             qq[j] = siluf_(q) * 0.08838834764831845f; kk[j] = 1.f - fg; lg[j] = __logf(fg); }
; #pragma unroll
;         for (int j = 1; j < 16; ++j) lg[j] += lg[j - 1];
;         part[jq * 128 + d] = lg[15];
;         sync_threads();
;         const float p0 = part[d], p1 = part[128 + d], p2 = part[256 + d], p3 = part[384 + d];
	v_exp_f32_e32 v89, v89
	v_mul_f32_e32 v116, v124, v116
	v_mul_f32_e32 v124, 0x3f317217, v125
	v_fma_f32 v124, v125, s74, -v124
	v_add_f32_e32 v89, 1.0, v89
	v_fmac_f32_e32 v124, 0x3377d1cf, v125
	v_rcp_f32_e32 v89, v89
	v_fmac_f32_e32 v124, 0x3f317217, v125
	v_cmp_lt_f32_e64 s[14:15], |v125|, s81
	v_lshlrev_b32_e32 v117, 16, v117
	v_fma_f32 v89, v110, v89, v93
	v_cndmask_b32_e64 v124, v125, v124, s[14:15]
	v_mul_f32_e32 v125, 0xbfb8aa3b, v117
	v_exp_f32_e32 v125, v125
	v_cndmask_b32_e32 v126, 0, v186, vcc
	v_cmp_gt_f32_e32 vcc, s33, v89
	v_sub_f32_e32 v124, v124, v126
	v_add_f32_e32 v125, 1.0, v125
	v_cndmask_b32_e64 v126, 0, 32, vcc
	v_ldexp_f32 v126, v89, v126
	v_lshlrev_b32_e32 v90, 16, v90
	v_rcp_f32_e32 v125, v125
	v_log_f32_e32 v126, v126
	v_mul_f32_e32 v90, 0xbfb8aa3b, v90
	v_exp_f32_e32 v90, v90
	v_mul_f32_e32 v117, v125, v117
	v_mul_f32_e32 v125, 0x3f317217, v126
	v_fma_f32 v125, v126, s74, -v125
	v_add_f32_e32 v90, 1.0, v90
	v_fmac_f32_e32 v125, 0x3377d1cf, v126
	v_rcp_f32_e32 v90, v90
	v_fmac_f32_e32 v125, 0x3f317217, v126
	v_cmp_lt_f32_e64 s[14:15], |v126|, s81
	v_lshlrev_b32_e32 v118, 16, v118
	v_fma_f32 v90, v110, v90, v93
	v_cndmask_b32_e64 v125, v126, v125, s[14:15]
	v_mul_f32_e32 v126, 0xbfb8aa3b, v118
	v_exp_f32_e32 v126, v126
	v_lshlrev_b32_e32 v91, 16, v91
	v_cndmask_b32_e32 v127, 0, v186, vcc
	v_cmp_gt_f32_e32 vcc, s33, v90
	v_mul_f32_e32 v91, 0xbfb8aa3b, v91
	v_sub_f32_e32 v125, v125, v127
	v_cndmask_b32_e64 v127, 0, 32, vcc
	v_exp_f32_e32 v91, v91
	v_add_f32_e32 v126, 1.0, v126
	v_ldexp_f32 v127, v90, v127
	v_rcp_f32_e32 v126, v126
	v_log_f32_e32 v127, v127
	v_add_f32_e32 v91, 1.0, v91
	v_lshlrev_b32_e32 v119, 16, v119
	v_rcp_f32_e32 v91, v91
	v_mul_f32_e32 v118, v126, v118
	v_mul_f32_e32 v126, 0x3f317217, v127
	v_mul_f32_e32 v128, 0xbfb8aa3b, v119
	v_fma_f32 v126, v127, s74, -v126
	v_exp_f32_e32 v128, v128
	v_fmac_f32_e32 v126, 0x3377d1cf, v127
	v_fmac_f32_e32 v126, 0x3f317217, v127
	v_cmp_lt_f32_e64 s[14:15], |v127|, s81
	v_fma_f32 v91, v110, v91, v93
	v_lshlrev_b32_e32 v111, 16, v111
	v_cndmask_b32_e64 v126, v127, v126, s[14:15]
	v_cmp_gt_f32_e64 s[14:15], s33, v91
	v_mul_f32_e32 v111, 0xbfb8aa3b, v111
	v_add_f32_e32 v127, 1.0, v128
	v_cndmask_b32_e64 v128, 0, 32, s[14:15]
	v_exp_f32_e32 v111, v111
	v_ldexp_f32 v128, v91, v128
	v_rcp_f32_e32 v127, v127
	v_log_f32_e32 v128, v128
	v_add_f32_e32 v111, 1.0, v111
	v_rcp_f32_e32 v111, v111
	v_mul_f32_e32 v119, v127, v119
	v_mul_f32_e32 v127, 0x3f317217, v128
	v_fma_f32 v127, v128, s74, -v127
	v_cndmask_b32_e32 v129, 0, v186, vcc
	v_fmac_f32_e32 v127, 0x3377d1cf, v128
	v_sub_f32_e32 v126, v126, v129
	v_fmac_f32_e32 v127, 0x3f317217, v128
	v_cmp_lt_f32_e64 vcc, |v128|, s81
	v_fma_f32 v129, v110, v111, v93
	v_lshlrev_b32_e32 v120, 16, v120
	v_cndmask_b32_e32 v127, v128, v127, vcc
	v_cmp_gt_f32_e32 vcc, s33, v129
	v_mul_f32_e32 v111, 0xbfb8aa3b, v120
	v_exp_f32_e32 v111, v111
	v_cndmask_b32_e64 v130, 0, 32, vcc
	v_ldexp_f32 v130, v129, v130
	v_log_f32_e32 v130, v130
	v_cndmask_b32_e64 v128, 0, v186, s[14:15]
	v_add_f32_e32 v111, 1.0, v111
	v_sub_f32_e32 v127, v127, v128
	v_rcp_f32_e32 v128, v111
	v_mul_f32_e32 v111, 0x3f317217, v130
	v_fma_f32 v111, v130, s74, -v111
	v_fmac_f32_e32 v111, 0x3377d1cf, v130
	v_fmac_f32_e32 v111, 0x3f317217, v130
	v_cmp_lt_f32_e64 s[14:15], |v130|, s81
	v_mul_f32_e32 v120, v128, v120
	v_sub_f32_e32 v62, 1.0, v62
	v_cndmask_b32_e64 v111, v130, v111, s[14:15]
	v_cndmask_b32_e32 v130, 0, v186, vcc
	v_sub_f32_e32 v111, v111, v130
	v_add_f32_e32 v130, v69, v78
	v_add_f32_e32 v131, v130, v79
	v_add_f32_e32 v132, v131, v80
	v_add_f32_e32 v133, v132, v81
	v_add_f32_e32 v82, v133, v82
	v_add_f32_e32 v83, v82, v83
	v_add_f32_e32 v84, v83, v84
	v_add_f32_e32 v121, v84, v121
	v_add_f32_e32 v122, v121, v122
	v_add_f32_e32 v123, v122, v123
	v_add_f32_e32 v124, v123, v124
	v_add_f32_e32 v125, v124, v125
	v_add_f32_e32 v126, v125, v126
	v_add_f32_e32 v127, v126, v127
	v_add_f32_e32 v134, v127, v111
	v_add_u32_e32 v111, v100, v112
	ds_write_b32 v109, v134 offset:52224
	s_waitcnt lgkmcnt(0)
	s_barrier
	ds_read2st64_b32 v[78:79], v111 offset0:204 offset1:206
	ds_read2st64_b32 v[80:81], v111 offset0:208 offset1:210
	v_mul_f32_e32 v67, 0x3db504f3, v67
	v_sub_f32_e32 v64, 1.0, v64
	v_mul_f32_e32 v70, 0x3db504f3, v70
	s_waitcnt lgkmcnt(0)
; __device__ __forceinline__ bf16 f2bf(float f) { return (bf16)pk2(f, f); }
; __device__ __forceinline__ float frcp_(float x) { return __builtin_amdgcn_rcpf(x); }
; #define LAS __attribute__((address_space(3)))
; __device__ __forceinline__ void hgrn_pass1(const RecurBufs& rb, const float* lbs_l, int u, int tid, LAS unsigned char* lds) {
;     ...
;         const float p0 = part[d], p1 = part[128 + d], p2 = part[256 + d], p3 = part[384 + d];
;         const float off = (jq > 0 ? p0 : 0.f) + (jq > 1 ? p1 : 0.f) + (jq > 2 ? p2 : 0.f);
;         const float bref = p0 + p1, bend = (p0 + p1) + (p2 + p3);
; #pragma unroll
;         for (int j = 0; j < 16; ++j) { const float e1 = __expf(fminf(fmaxf(off + lg[j] - bref, -80.f), 80.f));
;             *(LAS bf16*)(Qt + (16 * jq + j) * PQ + d * 2) = f2bf(qq[j] * e1); *(LAS bf16*)(Kt + (16 * jq + j) * PQ + d * 2) = f2bf(kk[j] * frcp_(e1)); }
	v_cndmask_b32_e64 v128, 0, v78, s[10:11]
	v_cndmask_b32_e64 v135, 0, v79, s[12:13]
	v_add_f32_e32 v128, v128, v135
	v_cndmask_b32_e64 v135, 0, v80, s[8:9]
	v_add_f32_e32 v128, v128, v135
	v_add_f32_e32 v78, v78, v79
	v_add_f32_e32 v69, v69, v128
	v_sub_f32_e32 v69, v69, v78
	v_med3_f32 v69, v69, s86, v187
	v_mul_f32_e32 v69, 0x3fb8aa3b, v69
	v_exp_f32_e32 v69, v69
	v_sub_f32_e32 v66, 1.0, v66
	v_mul_f32_e32 v72, 0x3db504f3, v72
	v_sub_f32_e32 v68, 1.0, v68
	v_mul_f32_e32 v63, v63, v69
	v_cvt_pk_bf16_f32 v63, v63, v63
	ds_write_b16 v98, v63
	v_rcp_f32_e32 v63, v69
	v_add_f32_e32 v69, v130, v128
	v_sub_f32_e32 v69, v69, v78
	v_med3_f32 v69, v69, s86, v187
	v_mul_f32_e32 v69, 0x3fb8aa3b, v69
	v_exp_f32_e32 v69, v69
	v_mul_f32_e32 v10, v10, v63
	v_cvt_pk_bf16_f32 v10, v10, v10
	ds_write_b16 v98, v10 offset:17408
	v_mul_f32_e32 v10, v65, v69
	v_add_f32_e32 v63, v131, v128
	v_cvt_pk_bf16_f32 v10, v10, v10
	v_sub_f32_e32 v63, v63, v78
	ds_write_b16 v98, v10 offset:272
	v_rcp_f32_e32 v10, v69
	v_med3_f32 v63, v63, s86, v187
	v_mul_f32_e32 v63, 0x3fb8aa3b, v63
	v_exp_f32_e32 v63, v63
	v_mul_f32_e32 v10, v62, v10
	v_cvt_pk_bf16_f32 v10, v10, v10
	ds_write_b16 v98, v10 offset:17680
	v_mul_f32_e32 v10, v67, v63
	v_add_f32_e32 v62, v132, v128
	v_cvt_pk_bf16_f32 v10, v10, v10
	v_sub_f32_e32 v62, v62, v78
	ds_write_b16 v98, v10 offset:544
	v_rcp_f32_e32 v10, v63
	v_med3_f32 v62, v62, s86, v187
	v_mul_f32_e32 v62, 0x3fb8aa3b, v62
	v_exp_f32_e32 v62, v62
	v_mul_f32_e32 v10, v64, v10
	v_cvt_pk_bf16_f32 v10, v10, v10
	ds_write_b16 v98, v10 offset:17952
	v_mul_f32_e32 v10, v70, v62
	v_cvt_pk_bf16_f32 v10, v10, v10
	ds_write_b16 v98, v10 offset:816
	v_rcp_f32_e32 v10, v62
	v_add_f32_e32 v62, v133, v128
	v_sub_f32_e32 v62, v62, v78
	v_med3_f32 v62, v62, s86, v187
	v_mul_f32_e32 v62, 0x3fb8aa3b, v62
	v_exp_f32_e32 v62, v62
	v_mul_f32_e32 v10, v66, v10
	v_cvt_pk_bf16_f32 v10, v10, v10
	ds_write_b16 v98, v10 offset:18224
	v_mul_f32_e32 v10, v72, v62
	v_cvt_pk_bf16_f32 v10, v10, v10
	ds_write_b16 v98, v10 offset:1088
	v_rcp_f32_e32 v10, v62
	v_add_f32_e32 v62, v82, v128
	v_sub_f32_e32 v62, v62, v78
	v_med3_f32 v62, v62, s86, v187
	v_mul_f32_e32 v62, 0x3fb8aa3b, v62
	v_exp_f32_e32 v62, v62
	v_mul_f32_e32 v10, v68, v10
	v_mul_f32_e32 v74, 0x3db504f3, v74
	v_cvt_pk_bf16_f32 v10, v10, v10
	ds_write_b16 v98, v10 offset:18496
	v_mul_f32_e32 v10, v74, v62
	v_cvt_pk_bf16_f32 v10, v10, v10
	ds_write_b16 v98, v10 offset:1360
	v_rcp_f32_e32 v10, v62
	v_add_f32_e32 v62, v83, v128
	v_sub_f32_e32 v62, v62, v78
	v_med3_f32 v62, v62, s86, v187
	v_mul_f32_e32 v62, 0x3fb8aa3b, v62
	v_exp_f32_e32 v62, v62
	v_sub_f32_e32 v71, 1.0, v71
	v_mul_f32_e32 v10, v71, v10
	v_mul_f32_e32 v75, 0x3db504f3, v75
	v_cvt_pk_bf16_f32 v10, v10, v10
	ds_write_b16 v98, v10 offset:18768
	v_mul_f32_e32 v10, v75, v62
	v_cvt_pk_bf16_f32 v10, v10, v10
	ds_write_b16 v98, v10 offset:1632
	v_rcp_f32_e32 v10, v62
	v_add_f32_e32 v62, v84, v128
	v_sub_f32_e32 v62, v62, v78
	v_med3_f32 v62, v62, s86, v187
	v_mul_f32_e32 v62, 0x3fb8aa3b, v62
	v_exp_f32_e32 v62, v62
	v_sub_f32_e32 v73, 1.0, v73
	v_mul_f32_e32 v10, v73, v10
	v_mul_f32_e32 v77, 0x3db504f3, v77
	v_cvt_pk_bf16_f32 v10, v10, v10
	ds_write_b16 v98, v10 offset:19040
	v_mul_f32_e32 v10, v77, v62
	v_cvt_pk_bf16_f32 v10, v10, v10
	ds_write_b16 v98, v10 offset:1904
	v_rcp_f32_e32 v10, v62
	v_add_f32_e32 v62, v121, v128
	v_sub_f32_e32 v62, v62, v78
	v_med3_f32 v62, v62, s86, v187
	v_mul_f32_e32 v62, 0x3fb8aa3b, v62
	v_exp_f32_e32 v62, v62
	v_sub_f32_e32 v76, 1.0, v76
	v_mul_f32_e32 v10, v76, v10
	v_mul_f32_e32 v113, 0x3db504f3, v113
	v_cvt_pk_bf16_f32 v10, v10, v10
	ds_write_b16 v98, v10 offset:19312
	v_mul_f32_e32 v10, v113, v62
	v_cvt_pk_bf16_f32 v10, v10, v10
	ds_write_b16 v98, v10 offset:2176
	v_rcp_f32_e32 v10, v62
	v_add_f32_e32 v62, v122, v128
	v_sub_f32_e32 v62, v62, v78
	v_med3_f32 v62, v62, s86, v187
; __device__ __forceinline__ bf16 f2bf(float f) { return (bf16)pk2(f, f); }
; __device__ __forceinline__ float frcp_(float x) { return __builtin_amdgcn_rcpf(x); }
; #define LAS __attribute__((address_space(3)))
; __device__ __forceinline__ void hgrn_pass1(const RecurBufs& rb, const float* lbs_l, int u, int tid, LAS unsigned char* lds) {
;     ...
;         const float off = (jq > 0 ? p0 : 0.f) + (jq > 1 ? p1 : 0.f) + (jq > 2 ? p2 : 0.f);
;         const float bref = p0 + p1, bend = (p0 + p1) + (p2 + p3);
; #pragma unroll
;         for (int j = 0; j < 16; ++j) { const float e1 = __expf(fminf(fmaxf(off + lg[j] - bref, -80.f), 80.f));
;             *(LAS bf16*)(Qt + (16 * jq + j) * PQ + d * 2) = f2bf(qq[j] * e1); *(LAS bf16*)(Kt + (16 * jq + j) * PQ + d * 2) = f2bf(kk[j] * frcp_(e1)); }
;         if (jq == 0) { const float eref = __expf(bref), esc = __expf(bend - bref), edc = __expf(bend);
;             float* cvp = rb.cv + ((size_t)((b * 8 + h) * 32 + seg * NCH + ch) * 3) * 128;
;             cvp[d] = eref; cvp[128 + d] = esc; cvp[256 + d] = edc; vec[128 + d] = esc; vec[256 + d] = edc; }
;         dprod *= __expf(bend);
	v_mul_f32_e32 v62, 0x3fb8aa3b, v62
	v_exp_f32_e32 v62, v62
	v_sub_f32_e32 v85, 1.0, v85
	v_mul_f32_e32 v10, v85, v10
	v_mul_f32_e32 v114, 0x3db504f3, v114
	v_cvt_pk_bf16_f32 v10, v10, v10
	ds_write_b16 v98, v10 offset:19584
	v_mul_f32_e32 v10, v114, v62
	v_cvt_pk_bf16_f32 v10, v10, v10
	ds_write_b16 v98, v10 offset:2448
	v_rcp_f32_e32 v10, v62
	v_add_f32_e32 v62, v123, v128
	v_sub_f32_e32 v62, v62, v78
	v_med3_f32 v62, v62, s86, v187
	v_mul_f32_e32 v62, 0x3fb8aa3b, v62
	v_exp_f32_e32 v62, v62
	v_sub_f32_e32 v86, 1.0, v86
	v_mul_f32_e32 v10, v86, v10
	v_mul_f32_e32 v115, 0x3db504f3, v115
	v_cvt_pk_bf16_f32 v10, v10, v10
	ds_write_b16 v98, v10 offset:19856
	v_mul_f32_e32 v10, v115, v62
	v_cvt_pk_bf16_f32 v10, v10, v10
	ds_write_b16 v98, v10 offset:2720
	v_rcp_f32_e32 v10, v62
	v_add_f32_e32 v62, v124, v128
	v_sub_f32_e32 v62, v62, v78
	v_med3_f32 v62, v62, s86, v187
	v_mul_f32_e32 v62, 0x3fb8aa3b, v62
	v_exp_f32_e32 v62, v62
	v_sub_f32_e32 v87, 1.0, v87
	v_mul_f32_e32 v10, v87, v10
	v_mul_f32_e32 v116, 0x3db504f3, v116
	v_cvt_pk_bf16_f32 v10, v10, v10
	ds_write_b16 v98, v10 offset:20128
	v_mul_f32_e32 v10, v116, v62
	v_cvt_pk_bf16_f32 v10, v10, v10
	ds_write_b16 v98, v10 offset:2992
	v_rcp_f32_e32 v10, v62
	v_add_f32_e32 v62, v125, v128
	v_sub_f32_e32 v62, v62, v78
	v_med3_f32 v62, v62, s86, v187
	v_mul_f32_e32 v62, 0x3fb8aa3b, v62
	v_exp_f32_e32 v62, v62
	v_sub_f32_e32 v88, 1.0, v88
	v_mul_f32_e32 v10, v88, v10
	v_mul_f32_e32 v117, 0x3db504f3, v117
	v_cvt_pk_bf16_f32 v10, v10, v10
	ds_write_b16 v98, v10 offset:20400
	v_mul_f32_e32 v10, v117, v62
	v_cvt_pk_bf16_f32 v10, v10, v10
	ds_write_b16 v98, v10 offset:3264
	v_rcp_f32_e32 v10, v62
	v_add_f32_e32 v62, v126, v128
	v_sub_f32_e32 v62, v62, v78
	v_med3_f32 v62, v62, s86, v187
	v_mul_f32_e32 v62, 0x3fb8aa3b, v62
	v_exp_f32_e32 v62, v62
	v_sub_f32_e32 v89, 1.0, v89
	v_mul_f32_e32 v10, v89, v10
	v_mul_f32_e32 v118, 0x3db504f3, v118
	v_cvt_pk_bf16_f32 v10, v10, v10
	ds_write_b16 v98, v10 offset:20672
	v_mul_f32_e32 v10, v118, v62
	v_cvt_pk_bf16_f32 v10, v10, v10
	ds_write_b16 v98, v10 offset:3536
	v_rcp_f32_e32 v10, v62
	v_add_f32_e32 v62, v128, v127
	v_sub_f32_e32 v62, v62, v78
	v_med3_f32 v62, v62, s86, v187
	v_mul_f32_e32 v62, 0x3fb8aa3b, v62
	v_exp_f32_e32 v62, v62
	v_sub_f32_e32 v90, 1.0, v90
	v_mul_f32_e32 v10, v90, v10
	v_mul_f32_e32 v119, 0x3db504f3, v119
	v_cvt_pk_bf16_f32 v10, v10, v10
	ds_write_b16 v98, v10 offset:20944
	v_mul_f32_e32 v10, v119, v62
	v_cvt_pk_bf16_f32 v10, v10, v10
	ds_write_b16 v98, v10 offset:3808
	v_rcp_f32_e32 v10, v62
	v_add_f32_e32 v62, v128, v134
	v_sub_f32_e32 v62, v62, v78
	v_med3_f32 v62, v62, s86, v187
	v_mul_f32_e32 v62, 0x3fb8aa3b, v62
	v_exp_f32_e32 v62, v62
	v_sub_f32_e32 v91, 1.0, v91
	v_mul_f32_e32 v10, v91, v10
	v_mul_f32_e32 v79, 0x3db504f3, v120
	v_add_f32_e32 v80, v80, v81
	v_cvt_pk_bf16_f32 v10, v10, v10
	ds_write_b16 v98, v10 offset:21216
	v_mul_f32_e32 v10, v79, v62
	v_rcp_f32_e32 v64, v62
	v_add_f32_e32 v62, v78, v80
	v_cvt_pk_bf16_f32 v10, v10, v10
	v_mul_f32_e32 v63, 0x3fb8aa3b, v62
	ds_write_b16 v98, v10 offset:4080
	v_exp_f32_e32 v10, v63
	v_sub_f32_e32 v120, 1.0, v129
	v_mul_f32_e32 v64, v120, v64
	v_cvt_pk_bf16_f32 v64, v64, v64
	ds_write_b16 v98, v64 offset:21488
	s_and_saveexec_b64 s[2:3], s[6:7]
	s_xor_b64 s[2:3], exec, s[2:3]
	v_exp_f32_e32 v10, v63
	s_andn2_saveexec_b64 s[2:3], s[2:3]
	s_cbranch_execz .LBB0_392
	v_sub_f32_e32 v62, v62, v78
	v_mul_f32_e32 v63, 0x3fb8aa3b, v78
	v_mul_f32_e32 v62, 0x3fb8aa3b, v62
	v_exp_f32_e32 v64, v63
	v_exp_f32_e32 v65, v62
	v_lshl_add_u64 v[62:63], s[72:73], 0, v[102:103]
	v_add_co_u32_e32 v62, vcc, 0x4d200000, v62
	s_nop 1
	v_addc_co_u32_e32 v63, vcc, 0, v63, vcc
	global_store_dword v[62:63], v64, off
	global_store_dword v[62:63], v65, off offset:512
	global_store_dword v[62:63], v10, off offset:1024
	ds_write2st64_b32 v111, v65, v10 offset0:214 offset1:216
	s_branch .LBB0_392

; #define LAUNDER_PTR(p) do {} while (0)
; #define LAUNDER_PTR(p) asm volatile("" : "+v"(p))
; __device__ __forceinline__ void hgrn_sample_load(f32x4 (&st)[8], const float* state_in, int bh, int tid) {
;     const float* sp = state_in + (size_t)bh * 16384 + tid * 4;
; #pragma unroll
;     for (int it = 0; it < 8; ++it) { LAUNDER_PTR(sp); st[it] = *(const f32x4*)sp; sp += 2048; }
; }
.LBB0_534:
	v_readlane_b32 s0, v255, 34
	v_readlane_b32 s4, v253, 15
	v_readlane_b32 s1, v255, 35
	v_readlane_b32 s5, v253, 16
	s_lshl_b64 s[2:3], s[0:1], 26
	v_readlane_b32 s8, v253, 19
	v_readlane_b32 s4, v254, 11
	v_readlane_b32 s9, v253, 20
	s_add_u32 s0, s8, s2
	v_readlane_b32 s5, v254, 12
	s_addc_u32 s1, s9, s3
	s_and_b64 vcc, exec, s[4:5]
	v_readlane_b32 s6, v253, 17
	v_readlane_b32 s7, v253, 18
	v_readlane_b32 s10, v253, 21
	v_readlane_b32 s11, v253, 22
	v_readlane_b32 s12, v253, 23
	v_readlane_b32 s13, v253, 24
	v_readlane_b32 s14, v253, 25
	v_readlane_b32 s15, v253, 26
	v_readlane_b32 s16, v253, 27
	v_readlane_b32 s17, v253, 28
	v_readlane_b32 s18, v253, 29
	v_readlane_b32 s19, v253, 30
	s_cbranch_vccz .LBB0_536
	s_waitcnt vmcnt(0) lgkmcnt(0)
	v_mov_b32_e32 v0, v138
	v_readlane_b32 s4, v255, 4
	v_readlane_b32 s5, v255, 5
	s_add_u32 s4, s0, s4
	v_lshlrev_b32_e32 v0, 2, v0
	s_addc_u32 s5, s1, s5
	v_ashrrev_i32_e32 v1, 31, v0
	v_lshl_add_u64 v[4:5], v[0:1], 2, s[4:5]
	global_load_dwordx4 v[0:3], v[4:5], off nt
	v_lshl_add_u64 v[8:9], v[4:5], 0, s[44:45]
	global_load_dwordx4 v[4:7], v[8:9], off nt
	v_lshl_add_u64 v[8:9], v[8:9], 0, s[44:45]
	global_load_dwordx4 v[12:15], v[8:9], off nt
	v_lshl_add_u64 v[8:9], v[8:9], 0, s[44:45]
	global_load_dwordx4 v[16:19], v[8:9], off nt
	v_lshl_add_u64 v[8:9], v[8:9], 0, s[44:45]
	global_load_dwordx4 v[20:23], v[8:9], off nt
	v_lshl_add_u64 v[8:9], v[8:9], 0, s[44:45]
	global_load_dwordx4 v[24:27], v[8:9], off nt
	v_lshl_add_u64 v[8:9], v[8:9], 0, s[44:45]
	global_load_dwordx4 v[28:31], v[8:9], off nt
	v_lshl_add_u64 v[8:9], v[8:9], 0, s[44:45]
	global_load_dwordx4 v[32:35], v[8:9], off nt

; #define LAS __attribute__((address_space(3)))
; __device__ __forceinline__ void hgrn_pass1(const RecurBufs& rb, const float* lbs_l, int u, int tid, LAS unsigned char* lds) {
;     const int b = u >> 5, h = (u >> 2) & 7, seg = u & 3, lane = tid & 63, w = tid >> 6;
;     const int d = tid & 127, jq = tid >> 7;
;     LAS unsigned char* Qt = lds + HG_QT; LAS unsigned char* Kt = lds + HG_KT; LAS unsigned char* V = lds + HG_V; LAS float* part = (LAS float*)(lds + HG_PART); LAS float* vec = (LAS float*)(lds + HG_VEC1);
;     const float lb = lbs_l[h * 128 + d];
;     f32x4 S[8];
; #pragma unroll
;     for (int et = 0; et < 8; ++et) S[et] = (f32x4){0.f, 0.f, 0.f, 0.f};
;     float dprod = 1.f;
;     const int sr = tid >> 4, sc16 = tid & 15;
;     v4u pre[6];
;     {   const bf16* gq = rb.proj + ((size_t)b * SEQ + seg * SEGLEN + sr) * LDP + PC_Q + h * 128 + sc16 * 8;
;         pre[0] = *(const v4u*)gq; pre[1] = *(const v4u*)(gq + 32 * (size_t)LDP); pre[2] = *(const v4u*)(gq + PC_F); pre[3] = *(const v4u*)(gq + 32 * (size_t)LDP + PC_F);
;         pre[4] = *(const v4u*)(gq + PC_I); pre[5] = *(const v4u*)(gq + 32 * (size_t)LDP + PC_I); }
.LBB0_539:
	s_bfe_u32 s4, s16, 0x30002
	v_mov_b32_e32 v97, v138
	s_lshl_b32 s17, s4, 7
	v_and_b32_e32 v92, 0x7f, v97
	s_and_b32 s3, s18, 3
	s_ashr_i32 s2, s16, 5
	s_waitcnt vmcnt(0) lgkmcnt(0)
	v_or_b32_e32 v0, s17, v92
	s_and_b32 s19, s16, 3
	s_lshl_b32 s14, s3, 3
	s_lshl_b32 s23, s3, 9
	s_ashr_i32 s3, s2, 31
	v_lshlrev_b32_e32 v10, 2, v0
	s_lshl_b32 s5, s19, 9
	s_lshl_b32 s9, s2, 8
	v_ashrrev_i32_e32 v2, 4, v97
	s_lshl_b64 s[2:3], s[2:3], 11
	v_lshl_add_u64 v[0:1], s[96:97], 0, v[10:11]
	s_lshl_b32 s8, s4, 5
	s_lshl_b32 s64, s4, 8
	s_or_b32 s4, s2, s5
	s_mov_b32 s5, s3
	v_ashrrev_i32_e32 v3, 31, v2
	global_load_dword v93, v[0:1], off
	v_mov_b64_e32 v[0:1], s[78:79]
	v_lshl_add_u64 v[4:5], s[4:5], 0, v[2:3]
	v_mad_u64_u32 v[94:95], s[4:5], v4, s77, v[0:1]
	v_and_b32_e32 v12, 15, v97
	v_mad_i32_i24 v95, v5, s77, v95
	v_lshlrev_b32_e32 v10, 4, v12
	v_lshl_add_u64 v[0:1], v[94:95], 0, s[64:65]
	v_lshl_add_u64 v[0:1], v[0:1], 0, v[10:11]
	s_mov_b32 s4, 0xc4000
	v_add_co_u32_e32 v4, vcc, s4, v0
	s_movk_i32 s4, 0x1000
	s_nop 0
	v_addc_co_u32_e32 v5, vcc, 0, v1, vcc
	v_add_co_u32_e32 v6, vcc, s4, v0
	s_mov_b32 s4, 0xc5000
	s_nop 0
	v_addc_co_u32_e32 v7, vcc, 0, v1, vcc
	v_add_co_u32_e32 v8, vcc, s4, v0
	global_load_dwordx4 v[36:39], v[0:1], off nt
	s_nop 0
	v_addc_co_u32_e32 v9, vcc, 0, v1, vcc
	global_load_dwordx4 v[44:47], v[4:5], off nt
	global_load_dwordx4 v[40:43], v[0:1], off offset:2048 nt
	global_load_dwordx4 v[48:51], v[4:5], off offset:2048 nt
	global_load_dwordx4 v[52:55], v[6:7], off nt
	global_load_dwordx4 v[56:59], v[8:9], off nt
	v_lshlrev_b32_e32 v8, 2, v97
	v_ashrrev_i32_e32 v1, 2, v97
	s_or_b32 s28, s9, s8
	s_movk_i32 s15, 0x110
	v_lshrrev_b32_e32 v5, 1, v97
	v_bfe_u32 v6, v97, 2, 2
	v_mul_lo_u32 v7, v2, s15
	v_lshlrev_b32_e32 v112, 1, v92
	v_and_b32_e32 v1, -16, v1
	v_and_b32_e32 v9, 12, v8
	s_or_b32 s14, s28, s14
	v_mov_b32_e32 v101, 1.0
	v_ashrrev_i32_e32 v0, 7, v97
	v_and_or_b32 v5, v5, 24, v6
	v_add_u32_e32 v6, 0, v7
	v_add_u32_e32 v100, 0, v112
	v_lshl_add_u32 v7, v1, 2, 0
	v_or_b32_e32 v1, v9, v1
	s_mul_hi_i32 s29, s14, 0x600
	s_mul_i32 s50, s14, 0x600
	s_movk_i32 s14, 0x1100
	s_or_b32 s2, s2, s23
	v_lshlrev_b32_e32 v96, 3, v12
	v_cmp_lt_i32_e64 s[10:11], 0, v0
	v_cmp_lt_i32_e64 s[12:13], 1, v0
	v_cmp_lt_i32_e64 s[8:9], 2, v0
	v_mul_u32_u24_e32 v13, 0x110, v5
	v_mad_u32_u24 v5, v5, s15, 0
	v_lshl_add_u32 v106, v12, 2, v7
	v_lshl_add_u32 v12, v1, 1, 0
	v_mad_u64_u32 v[98:99], s[14:15], v0, s14, v[100:101]
	v_lshl_add_u64 v[0:1], s[2:3], 0, v[2:3]
	v_mov_b64_e32 v[2:3], s[64:65]
	s_movk_i32 s4, 0x80
	s_movk_i32 s6, 0x7f
	v_and_b32_e32 v4, 48, v97
	v_lshlrev_b32_e32 v9, 1, v9
	v_mad_u64_u32 v[2:3], s[2:3], v0, s77, v[2:3]
	v_mov_b32_e32 v0, 0
	s_mov_b32 s22, 7
	v_cmp_gt_u32_e64 s[4:5], s4, v97
	v_cmp_lt_u32_e64 s[6:7], s6, v97
	v_add_u32_e32 v109, 0, v8
	v_lshl_or_b32 v102, v92, 2, s50
	v_mov_b32_e32 v103, s29
	v_mad_i32_i24 v105, v1, s77, v3
	v_or_b32_e32 v104, v2, v10
	v_add_u32_e32 v108, v6, v10
	v_add_u32_e32 v107, v7, v4
	v_add_u32_e32 v99, v12, v13
	v_add_u32_e32 v9, v5, v9
	s_waitcnt vmcnt(0) lgkmcnt(0)
	v_sub_f32_e32 v110, 1.0, v93
	v_mov_b32_e32 v1, v0
	v_mov_b32_e32 v2, v0
	v_mov_b32_e32 v3, v0
	v_mov_b32_e32 v4, v0
	v_mov_b32_e32 v5, v0
	v_mov_b32_e32 v6, v0
	v_mov_b32_e32 v7, v0
	v_mov_b32_e32 v12, v0
	v_mov_b32_e32 v13, v0
	v_mov_b32_e32 v14, v0
	v_mov_b32_e32 v15, v0
	v_mov_b32_e32 v16, v0
	v_mov_b32_e32 v17, v0
	v_mov_b32_e32 v18, v0
	v_mov_b32_e32 v19, v0
	v_mov_b32_e32 v20, v0
	v_mov_b32_e32 v21, v0
	v_mov_b32_e32 v22, v0
	v_mov_b32_e32 v23, v0
	v_mov_b32_e32 v24, v0
	v_mov_b32_e32 v25, v0
	v_mov_b32_e32 v26, v0
	v_mov_b32_e32 v27, v0
	v_mov_b32_e32 v28, v0
	v_mov_b32_e32 v29, v0
	v_mov_b32_e32 v30, v0
	v_mov_b32_e32 v31, v0
	v_mov_b32_e32 v32, v0
	v_mov_b32_e32 v33, v0
	v_mov_b32_e32 v34, v0
	v_mov_b32_e32 v35, v0
	s_branch .LBB0_541

; #define LAS __attribute__((address_space(3)))
; #define LAUNDER_PTR(p) do {} while (0)
; #define LAUNDER_PTR(p) asm volatile("" : "+v"(p))
; __device__ __forceinline__ void ssd_pass1(const RecurBufs& rb, const float* conv_w, const float* conv_b, const float* dt_bias, const float* a_log, float* conv_out_l, int u, int tid, LAS unsigned char* lds) {
;     ...
;         for (int i = 0; i < 8; ++i) *(LAS v4u*)(T + (rr + 8 * i) * PR + ch16 * 16) = raw[i];
;         if (ch + 1 < NCH) { const bf16* gp = rb.proj + (row0 + RC + rr) * LDP + PC_XBC + gcol;
; #pragma unroll
;             for (int i = 0; i < 8; ++i) { LAUNDER_PTR(gp); raw[i] = *(const v4u*)gp; gp += 8 * (size_t)LDP; } }
.LBB0_715:
	s_or_b64 exec, exec, s[70:71]
	s_cmp_eq_u32 s3, 7
	s_waitcnt vmcnt(0) lgkmcnt(0)
	ds_write_b128 v218, v[0:3]
	ds_write_b128 v218, v[4:7] offset:8320
	ds_write_b128 v218, v[12:15] offset:16640
	ds_write_b128 v218, v[16:19] offset:24960
	ds_write_b128 v218, v[20:23] offset:33280
	ds_write_b128 v218, v[24:27] offset:41600
	ds_write_b128 v218, v[28:31] offset:49920
	ds_write_b128 v218, v[32:35] offset:58240
	s_cbranch_scc1 .LBB0_717
	v_lshl_add_u64 v[0:1], v[124:125], 0, s[68:69]
	v_mov_b64_e32 v[2:3], s[78:79]
	v_mad_u64_u32 v[2:3], s[22:23], v0, s77, v[2:3]
	v_mov_b32_e32 v0, v3
	v_mad_u64_u32 v[0:1], s[22:23], v1, s77, v[0:1]
	v_mov_b32_e32 v3, v0
	v_lshl_add_u64 v[0:1], v[114:115], 1, v[2:3]
	v_lshl_add_u64 v[4:5], v[0:1], 0, s[92:93]
	global_load_dwordx4 v[0:3], v[4:5], off nt
	v_lshl_add_u64 v[12:13], v[4:5], 0, s[84:85]
	global_load_dwordx4 v[4:7], v[12:13], off nt
	v_lshl_add_u64 v[16:17], v[12:13], 0, s[84:85]
	global_load_dwordx4 v[12:15], v[16:17], off nt
	v_lshl_add_u64 v[20:21], v[16:17], 0, s[84:85]
	global_load_dwordx4 v[16:19], v[20:21], off nt
	v_lshl_add_u64 v[24:25], v[20:21], 0, s[84:85]
	global_load_dwordx4 v[20:23], v[24:25], off nt
	v_lshl_add_u64 v[28:29], v[24:25], 0, s[84:85]
	global_load_dwordx4 v[24:27], v[28:29], off nt
	v_lshl_add_u64 v[32:33], v[28:29], 0, s[84:85]
	global_load_dwordx4 v[28:31], v[32:33], off nt
	v_lshl_add_u64 v[32:33], v[32:33], 0, s[84:85]
	global_load_dwordx4 v[32:35], v[32:33], off nt
